# attention loop: LDS reads first in the MFMA segment (next-tile addresses formed in the pack phase), tile index / side test / K-aug word on SALU inside MFMA gaps, diagonal block out of line; stacked on
# baseline (speedup 1.0000x reference)
; #define ATT_DMA(i, slot) do { if (ABL & 1) break; const long off_ = (long)ATT_TAU(i) * KVBLK * INW; \
;         glds16(ksrc + off_, (unsigned)__builtin_amdgcn_readfirstlane(kdst + (slot) * SLOTB)); glds16(vsrc + off_, (unsigned)__builtin_amdgcn_readfirstlane(vdst + (slot) * SLOTB)); } while (0)
;     ...
;     for (int i = 1; i < NTe; ++i) {
;         const int tau = ATT_TAU(i), slot = i & 3;
;         { const int id_ = i + 2 < NTe ? i + 2 : NTe - 1; ATT_DMA(id_, (i + 2) & 3); }
;         { const lds_cptr vp = vp0 + ((i - 1) & 3) * SLOTB, kp = kp0 + slot * SLOTB;
.LBB0_334:
	v_lshlrev_b32_e32 v0, 5, v93
	v_and_b32_e32 v0, 32, v0
	v_or_b32_e32 v1, v172, v97
	v_add_u32_e32 v0, 0, v0
	v_lshlrev_b32_e32 v1, 6, v1
	v_mov_b32_e32 v15, 0
	v_add3_u32 v191, v0, v104, v1
	s_andn2_b64 vcc, exec, s[36:37]
	v_lshl_add_u32 v190, v170, 2, s20
	v_lshl_add_u32 v185, v172, 2, s20
	v_mov_b32_e32 v14, v15
	v_mov_b32_e32 v13, v15
	v_mov_b32_e32 v12, v15
	v_mov_b32_e32 v11, v15
	v_mov_b32_e32 v10, v15
	v_mov_b32_e32 v9, v15
	v_mov_b32_e32 v8, v15
	v_mov_b32_e32 v7, v15
	v_mov_b32_e32 v6, v15
	v_mov_b32_e32 v5, v15
	v_mov_b32_e32 v4, v15
	v_mov_b32_e32 v3, v15
	v_mov_b32_e32 v2, v15
	v_mov_b32_e32 v1, v15
	v_mov_b32_e32 v0, v15
	v_mov_b32_e32 v31, v15
	v_mov_b32_e32 v30, v15
	v_mov_b32_e32 v29, v15
	v_mov_b32_e32 v28, v15
	v_mov_b32_e32 v27, v15
	v_mov_b32_e32 v26, v15
	v_mov_b32_e32 v25, v15
	v_mov_b32_e32 v24, v15
	v_mov_b32_e32 v23, v15
	v_mov_b32_e32 v22, v15
	v_mov_b32_e32 v21, v15
	v_mov_b32_e32 v20, v15
	v_mov_b32_e32 v19, v15
	v_mov_b32_e32 v18, v15
	v_mov_b32_e32 v17, v15
	v_mov_b32_e32 v16, v15
	v_mov_b32_e32 v47, v15
	v_mov_b32_e32 v46, v15
	v_mov_b32_e32 v45, v15
	v_mov_b32_e32 v44, v15
	v_mov_b32_e32 v43, v15
	v_mov_b32_e32 v42, v15
	v_mov_b32_e32 v41, v15
	v_mov_b32_e32 v40, v15
	v_mov_b32_e32 v39, v15
	v_mov_b32_e32 v38, v15
	v_mov_b32_e32 v37, v15
	v_mov_b32_e32 v36, v15
	v_mov_b32_e32 v35, v15
	v_mov_b32_e32 v34, v15
	v_mov_b32_e32 v33, v15
	v_mov_b32_e32 v32, v15
	v_mov_b32_e32 v63, v15
	v_mov_b32_e32 v62, v15
	v_mov_b32_e32 v61, v15
	v_mov_b32_e32 v60, v15
	v_mov_b32_e32 v59, v15
	v_mov_b32_e32 v58, v15
	v_mov_b32_e32 v57, v15
	v_mov_b32_e32 v56, v15
	v_mov_b32_e32 v55, v15
	v_mov_b32_e32 v54, v15
	v_mov_b32_e32 v53, v15
	v_mov_b32_e32 v52, v15
	v_mov_b32_e32 v51, v15
	v_mov_b32_e32 v50, v15
	v_mov_b32_e32 v49, v15
	v_mov_b32_e32 v48, v15
	s_cbranch_vccnz .LBB0_368
	v_cvt_pk_bf16_f32 v4, v98, 0
	v_cndmask_b32_e64 v1, v175, v176, s[40:41]
	v_lshlrev_b32_e32 v4, 16, v4
	v_cndmask_b32_e64 v1, v1, 0, s[62:63]
	v_sub_f32_e32 v4, v98, v4
	v_cvt_pk_bf16_f32 v5, v4, 0
	v_cndmask_b32_e64 v128, 0, v1, s[38:39]
	v_cvt_pk_bf16_f32 v1, v99, 0
	v_cndmask_b32_e64 v2, v177, v178, s[40:41]
	v_lshlrev_b32_e32 v5, 16, v5
	v_lshlrev_b32_e32 v1, 16, v1
	v_cndmask_b32_e64 v2, v2, 0, s[62:63]
	v_sub_f32_e32 v5, v4, v5
	v_cvt_pk_bf16_f32 v4, v98, v4
	v_sub_f32_e32 v1, v99, v1
	v_cndmask_b32_e64 v126, v2, v4, s[38:39]
	v_cvt_pk_bf16_f32 v4, v1, 0
	v_cndmask_b32_e64 v0, v173, -v173, s[40:41]
	v_lshlrev_b32_e32 v4, 16, v4
	v_cndmask_b32_e64 v0, v0, 0, s[62:63]
	v_cndmask_b32_e64 v3, v179, v180, s[40:41]
	v_sub_f32_e32 v4, v1, v4
	v_cndmask_b32_e64 v3, v3, 0, s[62:63]
	v_cvt_pk_bf16_f32 v5, v5, v0
	v_cvt_pk_bf16_f32 v0, v4, v0
	s_or_b32 s21, s21, 64
	v_cndmask_b32_e64 v139, v3, v0, s[38:39]
	v_cvt_f32_u32_e32 v0, s21
	v_cvt_pk_bf16_f32 v1, v99, v1
	v_cndmask_b32_e64 v138, v2, v1, s[38:39]
	s_sub_i32 s20, 64, s14
	v_lshrrev_b32_e32 v1, 16, v0
	v_and_b32_e32 v0, 0x7fff0000, v0
	v_or_b32_e32 v0, v1, v0
	v_cndmask_b32_e64 v127, v3, v5, s[38:39]
	v_cndmask_b32_e64 v130, v0, v96, s[38:39]
	s_sub_i32 s27, s15, s23
	v_xor_b32_e32 v154, 0x80000000, v92
	v_mov_b32_e32 v0, 0
	v_mov_b64_e32 v[144:145], v[128:129]
	s_sub_i32 s19, 64, s23
	v_mov_b32_e32 v140, v128
	v_mov_b32_e32 v141, v129
	v_cndmask_b32_e64 v131, v1, v95, s[38:39]
	v_mov_b32_e32 v133, v129
	v_cndmask_b32_e64 v135, v1, v94, s[38:39]
	v_mov_b32_e32 v134, v130
	v_mov_b32_e32 v137, v129
	s_add_i32 s21, s22, s15
	s_add_i32 s22, s27, 63
	s_sub_i32 s23, 63, s14
	s_max_i32 s26, s20, 2
	v_mov_b32_e32 v156, v154
	v_mov_b32_e32 v157, v154
	s_add_i32 s27, s27, 62
	s_mov_b32 s28, 1
	s_mov_b32 s29, 0x8000
	v_mov_b64_e32 v[142:143], v[126:127]
	v_mov_b32_e32 v1, v0
	v_mov_b32_e32 v2, v0
	v_mov_b32_e32 v3, v0
	v_mov_b32_e32 v4, v0
	v_mov_b32_e32 v5, v0
	v_mov_b32_e32 v6, v0
	v_mov_b32_e32 v7, v0
	v_mov_b32_e32 v8, v0
	v_mov_b32_e32 v9, v0
	v_mov_b32_e32 v10, v0
	v_mov_b32_e32 v11, v0
	v_mov_b32_e32 v12, v0
	v_mov_b32_e32 v13, v0
	v_mov_b32_e32 v14, v0
	v_mov_b32_e32 v15, v0
	v_mov_b32_e32 v16, v0
	v_mov_b32_e32 v17, v0
	v_mov_b32_e32 v18, v0
	v_mov_b32_e32 v19, v0
	v_mov_b32_e32 v20, v0
	v_mov_b32_e32 v21, v0
	v_mov_b32_e32 v22, v0
	v_mov_b32_e32 v23, v0
	v_mov_b32_e32 v24, v0
	v_mov_b32_e32 v25, v0
	v_mov_b32_e32 v26, v0
	v_mov_b32_e32 v27, v0
	v_mov_b32_e32 v28, v0
	v_mov_b32_e32 v29, v0
	v_mov_b32_e32 v30, v0
	v_mov_b32_e32 v31, v0
	v_mov_b32_e32 v32, v0
	v_mov_b32_e32 v33, v0
	v_mov_b32_e32 v34, v0
	v_mov_b32_e32 v35, v0
	v_mov_b32_e32 v36, v0
	v_mov_b32_e32 v37, v0
	v_mov_b32_e32 v38, v0
	v_mov_b32_e32 v39, v0
	v_mov_b32_e32 v40, v0
	v_mov_b32_e32 v41, v0
	v_mov_b32_e32 v42, v0
	v_mov_b32_e32 v43, v0
	v_mov_b32_e32 v44, v0
	v_mov_b32_e32 v45, v0
	v_mov_b32_e32 v46, v0
	v_mov_b32_e32 v47, v0
	v_mov_b32_e32 v48, v0
	v_mov_b32_e32 v49, v0
	v_mov_b32_e32 v50, v0
	v_mov_b32_e32 v51, v0
	v_mov_b32_e32 v52, v0
	v_mov_b32_e32 v53, v0
	v_mov_b32_e32 v54, v0
	v_mov_b32_e32 v55, v0
	v_mov_b32_e32 v56, v0
	v_mov_b32_e32 v57, v0
	v_mov_b32_e32 v58, v0
	v_mov_b32_e32 v59, v0
	v_mov_b32_e32 v60, v0
	v_mov_b32_e32 v61, v0
	v_mov_b32_e32 v62, v0
	v_mov_b32_e32 v63, v0
	v_readfirstlane_b32 s100, v148
	v_readfirstlane_b32 s101, v149
	s_nop 1
	v_subrev_u32_e32 v146, s100, v146
	v_subrev_u32_e32 v148, s100, v148
	v_mov_b32_e32 v112, v191
	v_add_u32_e32 v197, 0x2000, v181
	v_add_u32_e32 v196, v197, v183
	s_branch .LBB0_339
; #define ATT_DIAG_BIAS(s0, s1) do { const float dqh_ = dq - (float)(4 * hi); _Pragma("unroll") for (int r = 0; r < 16; ++r) { const float c_ = (float)((r & 3) + 8 * (r >> 2)); \
;         s0[r] = __builtin_fmaf(-sl, __builtin_fabsf(dqh_ - c_), s0[r]); s1[r] = __builtin_fmaf(-sl, __builtin_fabsf(dqh_ - (c_ + 32.f)), s1[r]); } } while (0)
;     ...
;         { const bool diag = tau == td; const float dq = (float)(tq - tau * KVBLK);
;           if (ABL & 2) { asm volatile("" : "=v"(pa0), "=v"(pa1), "=v"(pa2), "=v"(pa3), "=v"(pb0), "=v"(pb1), "=v"(pb2), "=v"(pb3) : "v"(sa0), "v"(sa1), "v"(sb0), "v"(sb1)); } else {
;           if (diag) { ATT_DIAG_BIAS(sa0, sa1); ATT_DIAG_BIAS(sb0, sb1); }
.Latt_diag:
	s_lshl_b32 s34, s30, 6
	v_subrev_u32_e32 v128, s34, v171
	v_cvt_f32_i32_e32 v199, v128
	s_mov_b32 s34, 0xc2000000
	v_sub_f32_e32 v128, v199, v184
	s_mov_b32 s35, 0xc2040000
	v_pk_add_f32 v[158:159], v[128:129], s[34:35] op_sel_hi:[0,1]
	s_mov_b32 s34, -2.0
	s_mov_b32 s35, 0xc0400000
	v_pk_add_f32 v[160:161], v[128:129], s[34:35] op_sel_hi:[0,1]
	s_mov_b32 s34, 0xc2080000
	s_mov_b32 s35, 0xc20c0000
	v_pk_add_f32 v[162:163], v[128:129], s[34:35] op_sel_hi:[0,1]
	s_mov_b32 s34, 0xc1000000
	s_mov_b32 s35, 0xc1100000
	v_pk_add_f32 v[186:187], v[128:129], s[34:35] op_sel_hi:[0,1]
	s_mov_b32 s34, 0xc2200000
	s_mov_b32 s35, 0xc2240000
	v_pk_add_f32 v[188:189], v[128:129], s[34:35] op_sel_hi:[0,1]
	s_mov_b32 s34, 0xc1200000
	s_mov_b32 s35, 0xc1300000
	v_pk_add_f32 v[192:193], v[128:129], s[34:35] op_sel_hi:[0,1]
	s_mov_b32 s34, 0xc2280000
	s_mov_b32 s35, 0xc22c0000
	v_pk_add_f32 v[194:195], v[128:129], s[34:35] op_sel_hi:[0,1]
	s_mov_b32 s34, 0xc1800000
	s_mov_b32 s35, 0xc1880000
	v_pk_add_f32 v[200:201], v[128:129], s[34:35] op_sel_hi:[0,1]
	s_mov_b32 s34, 0xc2400000
	s_mov_b32 s35, 0xc2440000
	v_pk_add_f32 v[202:203], v[128:129], s[34:35] op_sel_hi:[0,1]
	s_mov_b32 s34, 0xc1900000
	s_mov_b32 s35, 0xc1980000
	v_pk_add_f32 v[204:205], v[128:129], s[34:35] op_sel_hi:[0,1]
	s_mov_b32 s34, 0xc2480000
	s_mov_b32 s35, 0xc24c0000
	v_pk_add_f32 v[206:207], v[128:129], s[34:35] op_sel_hi:[0,1]
	s_mov_b32 s34, 0xc1c00000
	s_mov_b32 s35, 0xc1c80000
	v_pk_add_f32 v[208:209], v[128:129], s[34:35] op_sel_hi:[0,1]
	s_mov_b32 s34, 0xc2600000
	s_mov_b32 s35, 0xc2640000
	v_pk_add_f32 v[210:211], v[128:129], s[34:35] op_sel_hi:[0,1]
	s_mov_b32 s34, 0xc1d00000
	s_mov_b32 s35, 0xc1d80000
	v_pk_add_f32 v[214:215], v[128:129], s[34:35] op_sel_hi:[0,1]
	s_mov_b32 s34, 0xc2680000
	s_mov_b32 s35, 0xc26c0000
	v_add_f32_e32 v155, -1.0, v128
	v_pk_add_f32 v[222:223], v[128:129], s[34:35] op_sel_hi:[0,1]
	v_and_b32_e32 v159, 0x7fffffff, v159
	v_and_b32_e32 v158, 0x7fffffff, v158
	v_and_b32_e32 v163, 0x7fffffff, v163
	v_and_b32_e32 v162, 0x7fffffff, v162
	v_and_b32_e32 v187, 0x7fffffff, v187
	v_and_b32_e32 v186, 0x7fffffff, v186
	v_and_b32_e32 v189, 0x7fffffff, v189
	v_and_b32_e32 v188, 0x7fffffff, v188
	v_and_b32_e32 v193, 0x7fffffff, v193
	v_and_b32_e32 v192, 0x7fffffff, v192
	v_and_b32_e32 v195, 0x7fffffff, v195
	v_and_b32_e32 v194, 0x7fffffff, v194
	v_and_b32_e32 v201, 0x7fffffff, v201
	v_and_b32_e32 v200, 0x7fffffff, v200
	v_and_b32_e32 v203, 0x7fffffff, v203
	v_and_b32_e32 v202, 0x7fffffff, v202
	v_and_b32_e32 v205, 0x7fffffff, v205
	v_and_b32_e32 v204, 0x7fffffff, v204
	v_and_b32_e32 v207, 0x7fffffff, v207
	v_and_b32_e32 v206, 0x7fffffff, v206
	v_and_b32_e32 v209, 0x7fffffff, v209
	v_and_b32_e32 v208, 0x7fffffff, v208
	v_and_b32_e32 v211, 0x7fffffff, v211
	v_and_b32_e32 v210, 0x7fffffff, v210
	v_and_b32_e32 v215, 0x7fffffff, v215
	v_and_b32_e32 v214, 0x7fffffff, v214
	v_and_b32_e32 v223, 0x7fffffff, v223
	v_and_b32_e32 v222, 0x7fffffff, v222
	v_and_b32_e32 v161, 0x7fffffff, v161
	v_and_b32_e32 v160, 0x7fffffff, v160
	v_and_b32_e32 v228, 0x7fffffff, v128
	v_and_b32_e32 v229, 0x7fffffff, v155
	v_mov_b32_e32 v155, v154
	v_pk_fma_f32 v[94:95], v[154:155], v[214:215], v[94:95]
	v_pk_fma_f32 v[92:93], v[154:155], v[208:209], v[92:93]
	v_pk_fma_f32 v[90:91], v[154:155], v[204:205], v[90:91]
	v_pk_fma_f32 v[88:89], v[154:155], v[200:201], v[88:89]
	v_pk_fma_f32 v[86:87], v[154:155], v[192:193], v[86:87]
	v_pk_fma_f32 v[84:85], v[154:155], v[186:187], v[84:85]
	v_pk_fma_f32 v[82:83], v[154:155], v[160:161], v[82:83]
	v_pk_fma_f32 v[80:81], v[156:157], v[228:229], v[80:81]
	v_pk_fma_f32 v[78:79], v[154:155], v[222:223], v[78:79]
	v_pk_fma_f32 v[76:77], v[154:155], v[210:211], v[76:77]
	v_pk_fma_f32 v[74:75], v[154:155], v[206:207], v[74:75]
	v_pk_fma_f32 v[72:73], v[154:155], v[202:203], v[72:73]
	v_pk_fma_f32 v[70:71], v[154:155], v[194:195], v[70:71]
	v_pk_fma_f32 v[68:69], v[154:155], v[188:189], v[68:69]
	v_pk_fma_f32 v[66:67], v[154:155], v[162:163], v[66:67]
	v_pk_fma_f32 v[64:65], v[156:157], v[158:159], v[64:65]
	v_pk_fma_f32 v[126:127], v[154:155], v[214:215], v[126:127]
	v_pk_fma_f32 v[124:125], v[154:155], v[208:209], v[124:125]
	v_pk_fma_f32 v[122:123], v[154:155], v[204:205], v[122:123]
	v_pk_fma_f32 v[120:121], v[154:155], v[200:201], v[120:121]
	v_pk_fma_f32 v[118:119], v[154:155], v[192:193], v[118:119]
	v_pk_fma_f32 v[116:117], v[154:155], v[186:187], v[116:117]
	v_pk_fma_f32 v[114:115], v[154:155], v[160:161], v[114:115]
	v_pk_fma_f32 v[112:113], v[156:157], v[228:229], v[112:113]
	v_pk_fma_f32 v[110:111], v[154:155], v[222:223], v[110:111]
	v_pk_fma_f32 v[108:109], v[154:155], v[210:211], v[108:109]
	v_pk_fma_f32 v[106:107], v[154:155], v[206:207], v[106:107]
	v_pk_fma_f32 v[104:105], v[154:155], v[202:203], v[104:105]
	v_pk_fma_f32 v[102:103], v[154:155], v[194:195], v[102:103]
	v_pk_fma_f32 v[100:101], v[154:155], v[188:189], v[100:101]
	v_pk_fma_f32 v[98:99], v[154:155], v[162:163], v[98:99]
	v_pk_fma_f32 v[96:97], v[156:157], v[158:159], v[96:97]
	s_branch .LBB0_341

; #define ATT_SB() __builtin_amdgcn_sched_barrier(0)
;     ...
;     for (int i = 1; i < NTe; ++i) {
;         const int tau = ATT_TAU(i), slot = i & 3;
;         { const int id_ = i + 2 < NTe ? i + 2 : NTe - 1; ATT_DMA(id_, (i + 2) & 3); }
;         { const lds_cptr vp = vp0 + ((i - 1) & 3) * SLOTB, kp = kp0 + slot * SLOTB;
;           ATT_VFR(a, 0); ATT_VFR(b, 1);
;           const bf16x8 ka0 = ATT_KA(0), ka1 = ATT_KA(2048), ka2 = ATT_KB(0), ka3 = ATT_KB(2048);
;           ATT_SB();
;           ATT_PVK(a, pa0, pb0); ATT_SB();
;           ATT_VFR(c, 2); ATT_SB();
;           ATT_PVK(b, pa1, pb1); ATT_SB();
;           ATT_VFR(d, 3);
;           const bf16x8 kb0 = ATT_KA(4096), kb1 = ATT_KA(6144), kb2 = ATT_KB(4096), kb3 = ATT_KB(6144);
;           ATT_LDQ();
;           ATT_SB();
;           ATT_PVK(c, pa2, pb2); ATT_SB();
;           ATT_PVK(d, pa3, pb3); ATT_SB();
;           ATT_QKA(); ATT_QKB(); }
;         ATT_SB();
;         ATT_BARV(2);
;         __builtin_amdgcn_s_setprio(1);
;         ATT_SB();
;         { const bool diag = tau == td; const float dq = (float)(tq - tau * KVBLK);
;           if (ABL & 2) { asm volatile("" : "=v"(pa0), "=v"(pa1), "=v"(pa2), "=v"(pa3), "=v"(pb0), "=v"(pb1), "=v"(pb2), "=v"(pb3) : "v"(sa0), "v"(sa1), "v"(sb0), "v"(sb1)); } else {
;           if (diag) { ATT_DIAG_BIAS(sa0, sa1); ATT_DIAG_BIAS(sb0, sb1); }
;           const float big = (float)(1u << THRL);
;           bool redo = false;
;           { float accA; ATT_EXPSUM(sa0, sa1, accA);
;             if (__builtin_expect(__any(!(accA < big)), 0)) { const lds_cptr kp = kp0 + slot * SLOTB;
;                 const bf16x8 ka0 = ATT_KA(0), ka1 = ATT_KA(2048), ka2 = ATT_KB(0), ka3 = ATT_KB(2048);
;                 ATT_LDQ();
;                 ATT_QKA(); asm volatile("s_nop 15\n\ts_nop 7" : "+v"(sa0), "+v"(sa1)); if (diag) ATT_DIAG_BIAS(sa0, sa1);
;                 accA = softmax_exact<false>(sa0, sa1, mhatA, lA, oa0, oa1, wsf, r32, hi); redo = true; }
;             lA += accA; ATT_PACK(sa0, sa1, pa0, pa1, pa2, pa3); }
;           ATT_SB();
;           { float accB; ATT_EXPSUM(sb0, sb1, accB);
;             if (__builtin_expect(__any(!(accB < big)), 0)) { const lds_cptr kp = kp0 + slot * SLOTB;
;                 const bf16x8 kb0 = ATT_KA(4096), kb1 = ATT_KA(6144), kb2 = ATT_KB(4096), kb3 = ATT_KB(6144);
;                 ATT_LDQ();
.LBB0_338:
	v_cvt_pk_bf16_f32 v103, v86, v87
	v_cvt_pk_bf16_f32 v86, v92, v93
	v_add_f32_e32 v153, v153, v79
	v_cvt_pk_bf16_f32 v100, v80, v81
	v_cvt_pk_bf16_f32 v101, v82, v83
	v_cvt_pk_bf16_f32 v102, v84, v85
	v_cvt_pk_bf16_f32 v84, v88, v97
	v_cvt_pk_bf16_f32 v85, v90, v99
	v_cvt_pk_bf16_f32 v87, v94, v73
	v_cvt_pk_bf16_f32 v80, v64, v65
	v_cvt_pk_bf16_f32 v81, v66, v67
	v_cvt_pk_bf16_f32 v82, v68, v69
	v_cvt_pk_bf16_f32 v83, v70, v71
	v_cvt_pk_bf16_f32 v64, v72, v89
	v_cvt_pk_bf16_f32 v65, v74, v91
	v_cvt_pk_bf16_f32 v66, v76, v77
	v_cvt_pk_bf16_f32 v67, v78, v75
	v_cvt_pk_bf16_f32 v88, v193, v158
	v_cvt_pk_bf16_f32 v89, v194, v112
	v_cvt_pk_bf16_f32 v90, v195, v114
	v_cvt_pk_bf16_f32 v91, v198, v160
	v_cvt_pk_bf16_f32 v76, v161, v162
	v_cvt_pk_bf16_f32 v77, v163, v120
	v_cvt_pk_bf16_f32 v78, v121, v122
	v_cvt_pk_bf16_f32 v79, v123, v124
	v_cvt_pk_bf16_f32 v72, v192, v128
	v_cvt_pk_bf16_f32 v73, v159, v96
	v_cvt_pk_bf16_f32 v74, v113, v98
	v_cvt_pk_bf16_f32 v75, v115, v116
	v_cvt_pk_bf16_f32 v68, v117, v118
	v_cvt_pk_bf16_f32 v69, v119, v104
	v_cvt_pk_bf16_f32 v70, v105, v106
	v_cvt_pk_bf16_f32 v71, v107, v108
	v_add_f32_e32 v152, v152, v109
	s_and_b32 vcc_lo, s29, 0x6000
	s_add_i32 vcc_hi, s29, 0x2000
	s_and_b32 vcc_hi, vcc_hi, 0x6000
	v_add_u32_e32 v112, vcc_lo, v191
	v_add_u32_e32 v197, vcc_hi, v181
	v_add_u32_e32 v196, v197, v183
	s_mul_i32 vcc_lo, s98, 0x10001
	s_mov_b32 exec_lo, 0
	v_mov_b32_e32 v130, vcc_lo
	v_mov_b32_e32 v131, s98
	v_mov_b32_e32 v134, vcc_lo
	v_mov_b32_e32 v135, s98
	s_mov_b32 exec_lo, -1
	s_setprio 0
	s_waitcnt lgkmcnt(0)
	s_barrier
	s_cmp_eq_u32 s28, s26
	s_cbranch_scc1 .LBB0_367
.LBB0_339:
	ds_read_b64_tr_b16 v[92:93], v112 offset:32768
	ds_read_b64_tr_b16 v[94:95], v112 offset:33280
	ds_read_b64_tr_b16 v[96:97], v112 offset:33792
	ds_read_b64_tr_b16 v[98:99], v112 offset:34304
	ds_read_b64_tr_b16 v[104:105], v112 offset:36864
	ds_read_b64_tr_b16 v[106:107], v112 offset:37376
	ds_read_b64_tr_b16 v[108:109], v112 offset:37888
	ds_read_b64_tr_b16 v[110:111], v112 offset:38400
	ds_read_b128 v[158:161], v197
	ds_read_b128 v[192:195], v197 offset:2048
	ds_read_b128 v[198:201], v196
	ds_read_b128 v[202:205], v196 offset:2048
	s_add_i32 s30, s15, s28
	s_cmp_lt_i32 s28, s19
	s_cselect_b32 s30, s30, s27
	s_add_i32 s36, s28, 2
	s_cmp_lt_i32 s36, s20
	s_cselect_b32 s34, s36, s23
	s_add_i32 s35, s34, s15
	s_sub_i32 s36, s22, s34
	s_cmp_lt_i32 s34, s19
	s_cselect_b32 s36, s35, s36
	s_waitcnt lgkmcnt(10)
	v_mfma_f32_32x32x16_bf16 v[48:63], v[88:91], v[92:95], v[48:63]
	s_mul_i32 s34, s36, 0x50000
	s_add_u32 s34, s100, s34
	s_addc_u32 s35, s101, 0
	s_add_i32 s37, s29, 0xffffe000
	s_and_b32 s37, s37, 0x6000
	s_waitcnt lgkmcnt(6)
	v_mfma_f32_32x32x16_bf16 v[32:47], v[88:91], v[104:107], v[32:47]
	s_add_i32 s31, s28, 1
	s_cmp_lt_i32 s31, s20
	s_cselect_b32 s31, s31, s28
	s_add_i32 s98, s31, s15
	v_mfma_f32_32x32x16_bf16 v[16:31], v[100:103], v[92:95], v[16:31]
	s_sub_i32 s99, s22, s31
	s_cmp_lt_i32 s31, s19
	s_cselect_b32 s31, s98, s99
	v_mfma_f32_32x32x16_bf16 v[0:15], v[100:103], v[104:107], v[0:15]
	ds_read_b64_tr_b16 v[88:89], v112 offset:34816
	ds_read_b64_tr_b16 v[90:91], v112 offset:35328
	ds_read_b64_tr_b16 v[92:93], v112 offset:38912
	ds_read_b64_tr_b16 v[94:95], v112 offset:39424
	v_mfma_f32_32x32x16_bf16 v[48:63], v[76:79], v[96:99], v[48:63]
	s_add_i32 m0, s37, s45
	s_nop 0
	global_load_lds_dwordx4 v148, s[34:35]
	s_add_i32 m0, s37, s18
	s_nop 0
	global_load_lds_dwordx4 v146, s[34:35]
	s_waitcnt lgkmcnt(8)
	v_mfma_f32_32x32x16_bf16 v[32:47], v[76:79], v[108:111], v[32:47]
	s_sub_i32 s98, s30, s21
	s_sub_i32 s99, s31, s21
	s_mul_i32 s99, s98, s99
	s_addk_i32 s29, 0x2000
	s_add_i32 s27, s27, -1
	v_mfma_f32_32x32x16_bf16 v[16:31], v[84:87], v[96:99], v[16:31]
	s_add_i32 s28, s28, 1
	s_flbit_i32_b32 s34, s31
	s_sub_i32 s35, s34, 24
	s_lshl_b32 s35, s31, s35
	s_sub_i32 s34, 0xa3, s34
	v_mfma_f32_32x32x16_bf16 v[0:15], v[84:87], v[108:111], v[0:15]
	ds_read_b64_tr_b16 v[76:77], v112 offset:35840
	ds_read_b64_tr_b16 v[78:79], v112 offset:36352
	ds_read_b64_tr_b16 v[84:85], v112 offset:39936
	ds_read_b64_tr_b16 v[86:87], v112 offset:40448
	ds_read_b128 v[206:209], v197 offset:4096
	ds_read_b128 v[228:231], v197 offset:6144
	ds_read_b128 v[232:235], v196 offset:4096
	ds_read_b128 v[236:239], v196 offset:6144
	ds_read_b128 v[240:243], v174
	ds_read_b128 v[244:247], v174 offset:1024
	ds_read_b128 v[248:251], v174 offset:2048
	ds_read_b128 v[186:189], v174 offset:3072
	s_waitcnt lgkmcnt(14)
	v_mfma_f32_32x32x16_bf16 v[48:63], v[72:75], v[88:91], v[48:63]
	s_waitcnt lgkmcnt(12)
	v_mfma_f32_32x32x16_bf16 v[32:47], v[72:75], v[92:95], v[32:47]
	s_lshl_b32 s34, s34, 7
	s_add_i32 s34, s34, s35
	s_cmp_eq_u32 s31, 0
	s_cselect_b32 s98, 0, s34
	v_mfma_f32_32x32x16_bf16 v[16:31], v[80:83], v[88:91], v[16:31]
	v_mfma_f32_32x32x16_bf16 v[0:15], v[80:83], v[92:95], v[0:15]
	s_waitcnt lgkmcnt(10)
	v_mfma_f32_32x32x16_bf16 v[48:63], v[68:71], v[76:79], v[48:63]
	s_waitcnt lgkmcnt(8)
	v_mfma_f32_32x32x16_bf16 v[32:47], v[68:71], v[84:87], v[32:47]
	v_mfma_f32_32x32x16_bf16 v[16:31], v[64:67], v[76:79], v[16:31]
	v_mfma_f32_32x32x16_bf16 v[0:15], v[64:67], v[84:87], v[0:15]
	v_mfma_f32_32x32x16_bf16 v[112:127], v[134:137], v[142:145], 0
	v_mfma_f32_32x32x16_bf16 v[96:111], v[130:133], v[142:145], 0
	v_mfma_f32_32x32x16_bf16 v[80:95], v[134:137], v[138:141], 0
	v_mfma_f32_32x32x16_bf16 v[64:79], v[130:133], v[138:141], 0
	s_waitcnt lgkmcnt(3)
	v_mfma_f32_32x32x16_bf16 v[112:127], v[158:161], v[240:243], v[112:127]
	v_mfma_f32_32x32x16_bf16 v[96:111], v[192:195], v[240:243], v[96:111]
	s_waitcnt lgkmcnt(1)
	v_mfma_f32_32x32x16_bf16 v[80:95], v[206:209], v[248:251], v[80:95]
	v_mfma_f32_32x32x16_bf16 v[64:79], v[228:231], v[248:251], v[64:79]
	v_mfma_f32_32x32x16_bf16 v[112:127], v[198:201], v[244:247], v[112:127]
	v_mfma_f32_32x32x16_bf16 v[96:111], v[202:205], v[244:247], v[96:111]
	s_waitcnt lgkmcnt(0)
	v_mfma_f32_32x32x16_bf16 v[80:95], v[232:235], v[186:189], v[80:95]
	v_mfma_f32_32x32x16_bf16 v[64:79], v[236:239], v[186:189], v[64:79]
	s_cmp_eq_u32 s30, s21
	s_cselect_b64 s[42:43], -1, 0
	s_cmp_lg_u32 s30, s21
	s_waitcnt vmcnt(2) lgkmcnt(0)
	s_barrier
	s_setprio 1
	s_nop 1
	s_cbranch_scc0 .Latt_diag

; #define ATT_KAUG(tau_) do { const unsigned tb_ = __float_as_uint((float)((tau_) * KVBLK)) >> 16; \
;         if (hi) { const u32x4 w_ = (u32x4){tb_ | (tb_ << 16), tb_, 0u, 0u}; kaug0 = __builtin_bit_cast(bf16x8, w_); kaug1 = kaug0; } } while (0)
;     ...
;           { const int in_ = i + 1 < NTe ? i + 1 : i; const int tn_ = ATT_TAU(in_); const int sdn_ = ATT_SIDE(tn_);
;             if (redo || sdn_ != ATT_SIDE(tau)) { ATT_QAUG(sdn_); }
;             ATT_KAUG(tn_); } } }
.LBB0_343:
	s_cmp_lt_i32 s99, 1
	s_cbranch_scc1 .Latt_side_slow
	s_and_b64 vcc, exec, s[62:63]
	s_mov_b64 s[34:35], s[74:75]
	s_cbranch_vccz .LBB0_338
